# v38 + dense unit prologue only (mref once per phase, K2 DMA before Q wait)
# speedup vs baseline: 1.0031x; 1.0031x over previous
; __global__ void __launch_bounds__(512) mega_fwd(Args args) {
;     ...
;         if (IN_(ph)) {
;             for (int rep = 0; rep < PROBE_DENSE; ++rep)
;             for (int ui = 0, u = blockIdx.x; u < 768; u += G, ++ui) {
;                 int qb = u & 63, h3 = (u >> 6) % 3, kvh = (u / 192) & 1, b = u / 384;
;                 if (G == 256) { const int xcd = blockIdx.x & 7, j = blockIdx.x >> 3;
;                     b = (xcd >> 1) & 1; kvh = xcd & 1; h3 = ui; qb = (xcd >> 2) * 32 + j; }
;                 attn_body::attn_unit<8>(b, kvh * 3 + h3, qb, (const attn_body::bf16*)(QKV + pg8::OFF_QC), (const attn_body::bf16*)(QKV + pg8::OFF_KC),
;                                         (const attn_body::bf16*)(QKV + pg8::OFF_VC), (attn_body::bf16*)(YB + 640), GSS + (size_t)(l * 3 + 2) * MT, ((const float*)(ws + WS_MREF))[l], (char*)lds_raw);
.LBB0_440:
	s_andn2_b64 vcc, exec, s[0:1]
	s_cbranch_vccnz .LBB0_779
	s_mul_i32 s34, s60, 0x18000
	s_lshl_b64 s[0:1], s[34:35], 2
	v_readlane_b32 s4, v252, 49
	s_add_u32 s6, s4, s0
	v_readlane_b32 s0, v252, 50
	s_addc_u32 s7, s0, s1
	v_readlane_b32 s0, v253, 50
	v_readlane_b32 s1, v253, 51
	s_andn2_b64 vcc, exec, s[0:1]
	s_nop 0
	v_cndmask_b32_e64 v0, 0, 1, s[0:1]
	v_cmp_ne_u32_e64 s[38:39], 1, v0
	s_cbranch_vccnz .LBB0_461
	s_add_u32 s8, s6, 0x40000
	s_addc_u32 s9, s7, 0
	s_lshl_b64 s[0:1], s[60:61], 2
	v_readlane_b32 s4, v254, 1
	s_add_u32 s0, s4, s0
	v_readlane_b32 s4, v254, 2
	s_addc_u32 s1, s4, s1
	s_mov_b32 s10, 0
	s_mov_b32 s11, s90
	global_load_dword v225, v129, s[0:1]
	s_branch .LBB0_444

; #define WAIT_BAR(N) asm volatile("s_waitcnt vmcnt(" #N ") lgkmcnt(0)\n\ts_barrier":::"memory")
;   #define DMA_K(t,slot) glds16(ksrc+(long)(t)*KVBLK*KP,(unsigned)__builtin_amdgcn_readfirstlane(kdst+(slot)))
;   #define DMA_V(t,slot) glds16(vsrc+(long)(t)*KVBLK*KP,(unsigned)__builtin_amdgcn_readfirstlane(vdst+(slot)))
;   #define CMASK(P0,P1,t) do{}while(0)
;   #define START(P0,P1) do{ _Pragma("unroll") for(int r=0;r<16;++r)P0[r]=__builtin_amdgcn_exp2f(P0[r]); }while(0)
;   #define CMASK(P0,P1,t) do{}while(0)
;   #define CMASK(P0,P1,t) do{}while(0)
; template<int THRL> __device__ __forceinline__ void attn_unit(int b,int h,int qb,const bf16*Q,const bf16*__restrict__ K,const bf16*__restrict__ V,bf16*O,float*gssrow,float mref,char*shm){
;   int tid_l=threadIdx.x; asm volatile("":"+v"(tid_l)); const int tid=tid_l,lane=tid&63,r32=lane&31,hi=lane>>5; const int wid=__builtin_amdgcn_readfirstlane(tid>>6);
;   const long rowbase=(long)b*SEQ; const int q0=qb*QB;
;   const bf16*Qw=Q+(rowbase+q0+wid*QBLK)*QP+h*D;
;   const int g=h/3; const bf16*Kh=K+rowbase*KP+g*D,*Vh=V+rowbase*KP+g*D;
;   const unsigned lds0=(unsigned)(uintptr_t)shm;
;   float*wsf=(float*)(shm+LDS_WS)+wid*64;
;   const bf16*ksrc=Kh+(long)lane*KP+wid*8;
;   const bf16*vsrc=Vh+(long)(16*(wid&3)+(lane>>2))*KP+(wid>>2)*32+(lane&3)*8;
;   const unsigned kdst=lds0+LDS_K+wid*1024, vdst=lds0+LDS_V+wid*1024;
;     ...
;   const int vb0=(int)(lds0+LDS_V)+((lane>>4)&1)*32+(lane&3)*8+(4*hi+((lane&15)>>2))*64;
;   const char*Kbase=shm+LDS_K; bf16x8 kf[8];
;   const lds_cptr shm3=(lds_cptr)shm; const lds_cptr kp0=shm3+LDS_K+hi*1024+r32*16; const lds_cptr vp0=shm3+LDS_V+((lane>>4)&1)*32+(lane&3)*8+(4*hi+((lane&15)>>2))*64;
;   const int NT=SEQ/KVBLK;
;   DMA_K(0,0);DMA_V(0,0);DMA_K(1,SLOTB);
;   bf16x8 qr[4];
;   #pragma unroll
;   for(int d0=0;d0<4;++d0)qr[d0]=*reinterpret_cast<const bf16x8*>(&Qw[(long)r32*QP+d0*16+hi*8]);
;   float l_reg=0.f;f32x16 o[2];o[0]=f32x16{};o[1]=f32x16{};f32x16 negm;_Pragma("unroll") for(int r=0;r<16;++r)negm[r]=-mref;asm volatile("":"+v"(negm));
;     ...
;   f32x16 pA0,pA1,pB0,pB1;
;   int sl_prev=0,sl_cur=0,sl_next=SLOTB;
;     ...
;   DMA_K(2,2*SLOTB);
;   WAIT_BAR(3);
;   qkt(pA0,pA1,Kbase,qr,negm,r32,hi);asm volatile("s_nop 15\n\ts_nop 7":"+v"(pA0),"+v"(pA1));CMASK(pA0,pA1,0);
;   START(pA0,pA1);
;   _Pragma("unroll") for(int r=0;r<16;++r)pA1[r]=__builtin_amdgcn_exp2f(pA1[r]);
;   WAIT_BAR(0);
.LBB0_447:
	s_bitcmp1_b32 s14, 0
	s_cselect_b32 s14, 3, 0
	v_mov_b32_e32 v194, v226
	s_add_i32 s29, s14, s5
	s_ashr_i32 s5, s4, 31
	v_readfirstlane_b32 s15, v194
	s_ashr_i32 s14, s15, 6
	s_lshl_b64 s[42:43], s[4:5], 14
	s_lshl_b32 s34, s20, 8
	s_add_u32 s20, s42, s34
	s_addc_u32 s21, s43, 0
	s_lshl_b32 s40, s14, 5
	s_ashr_i32 s41, s40, 31
	s_add_u32 s46, s20, s40
	s_addc_u32 s47, s21, s41
	s_mul_i32 s20, s47, 0x300
	s_mul_hi_u32 s21, s46, 0x300
	s_add_i32 s21, s21, s20
	s_mul_i32 s20, s46, 0x300
	v_readlane_b32 s12, v253, 57
	s_add_u32 s30, s12, s20
	v_readlane_b32 s12, v253, 58
	s_addc_u32 s31, s12, s21
	s_lshl_b32 s20, s29, 6
	s_ashr_i32 s21, s20, 31
	s_lshl_b64 s[44:45], s[20:21], 1
	s_add_u32 s20, s30, s44
	s_mul_hi_i32 s29, s29, 0x55555556
	s_addc_u32 s21, s31, s45
	s_lshr_b32 s30, s29, 31
	s_add_i32 s29, s29, s30
	s_lshl_b64 s[48:49], s[4:5], 22
	v_readlane_b32 s4, v253, 59
	s_add_u32 s30, s4, s48
	v_readlane_b32 s4, v253, 60
	s_addc_u32 s31, s4, s49
	s_lshl_b32 s4, s29, 6
	s_ashr_i32 s5, s4, 31
	s_lshl_b64 s[50:51], s[4:5], 1
	s_add_u32 s4, s30, s50
	s_addc_u32 s5, s31, s51
	v_readlane_b32 s12, v253, 61
	s_add_u32 s29, s12, s48
	v_readlane_b32 s12, v253, 62
	s_addc_u32 s31, s12, s49
	v_and_b32_e32 v195, 63, v194
	s_add_u32 s30, s29, s50
	s_addc_u32 s31, s31, s51
	v_lshlrev_b32_e32 v128, 8, v195
	s_lshl_b32 s54, s14, 3
	s_waitcnt lgkmcnt(0)
	v_lshl_add_u64 v[0:1], s[4:5], 0, v[128:129]
	s_ashr_i32 s55, s54, 31
	s_lshl_b32 s4, s14, 4
	v_bfe_u32 v84, v194, 2, 4
	v_lshl_add_u64 v[188:189], s[54:55], 1, v[0:1]
	v_and_or_b32 v0, s4, 48, v84
	s_ashr_i32 s4, s15, 3
	s_and_b32 s52, s4, 0xffffffe0
	s_ashr_i32 s53, s52, 31
	s_lshl_b32 s5, s14, 10
	v_lshlrev_b32_e32 v0, 8, v0
	v_mov_b32_e32 v1, v129
	v_lshlrev_b32_e32 v2, 3, v194
	s_cmp_lg_u32 0, -1
	v_lshl_add_u64 v[0:1], s[30:31], 0, v[0:1]
	v_and_b32_e32 v201, 24, v2
	s_cselect_b32 s4, 0, 0
	v_lshl_add_u64 v[0:1], s[52:53], 1, v[0:1]
	v_lshlrev_b32_e32 v2, 1, v201
	v_mov_b32_e32 v3, v129
	s_add_i32 s5, s5, s4
	s_mov_b32 s29, m0
	s_mov_b32 m0, s5
	s_nop 0
	global_load_lds_dwordx4 v[188:189], off
	s_mov_b32 m0, s29
	v_and_b32_e32 v196, 31, v194
	v_lshl_add_u64 v[186:187], v[0:1], 0, v[2:3]
	s_add_i32 s4, s5, 0x6000
	s_mov_b32 s29, m0
	s_mov_b32 m0, s4
	s_nop 0
	global_load_lds_dwordx4 v[186:187], off
	s_mov_b32 m0, s29
	v_lshl_add_u64 v[0:1], v[188:189], 0, s[26:27]
	s_add_i32 s29, s5, 0x2000
	s_mov_b32 s30, m0
	s_mov_b32 m0, s29
	s_nop 0
	global_load_lds_dwordx4 v[0:1], off
	s_mov_b32 m0, s30
	v_mul_u32_u24_e32 v0, 0x180, v196
	v_bfe_u32 v197, v194, 5, 1
	v_lshlrev_b32_e32 v0, 1, v0
	v_lshl_or_b32 v2, v197, 4, v0
	global_load_dwordx4 v[158:161], v2, s[20:21]
	global_load_dwordx4 v[150:153], v2, s[20:21] offset:32
	global_load_dwordx4 v[142:145], v2, s[20:21] offset:64
	global_load_dwordx4 v[134:137], v2, s[20:21] offset:96
	v_lshl_add_u64 v[0:1], v[188:189], 0, s[24:25]
	s_add_i32 s29, s5, 0x4000
	s_mov_b32 s30, m0
	s_mov_b32 m0, s29
	s_nop 0
	global_load_lds_dwordx4 v[0:1], off
	s_mov_b32 m0, s30
	s_waitcnt vmcnt(0)
	v_xor_b32_e32 v32, 0x80000000, v225
	v_lshlrev_b32_e32 v0, 10, v197
	v_lshlrev_b32_e32 v1, 4, v196
	v_mov_b32_e32 v33, v32
	v_mov_b32_e32 v34, v32
	v_mov_b32_e32 v35, v32
	v_mov_b32_e32 v36, v32
	v_mov_b32_e32 v37, v32
	v_mov_b32_e32 v38, v32
	v_mov_b32_e32 v39, v32
	v_mov_b32_e32 v40, v32
	v_mov_b32_e32 v41, v32
	v_mov_b32_e32 v42, v32
	v_mov_b32_e32 v43, v32
	v_mov_b32_e32 v44, v32
	v_mov_b32_e32 v45, v32
	v_mov_b32_e32 v46, v32
	v_mov_b32_e32 v47, v32
	v_add3_u32 v200, 0, v0, v1
	s_waitcnt vmcnt(3) lgkmcnt(0)
	s_barrier
	ds_read_b128 v[0:3], v200
	ds_read_b128 v[48:51], v200 offset:512
	s_add_i32 s20, s5, 0x8000
	s_cmp_gt_i32 s14, 3
	s_waitcnt lgkmcnt(1)
	v_mfma_f32_32x32x16_bf16 v[16:31], v[0:3], v[158:161], v[32:47]
	s_waitcnt lgkmcnt(0)
	v_mfma_f32_32x32x16_bf16 v[0:15], v[48:51], v[158:161], v[32:47]
	ds_read_b128 v[48:51], v200 offset:2048
	ds_read_b128 v[52:55], v200 offset:2560
	s_waitcnt lgkmcnt(1)
	v_mfma_f32_32x32x16_bf16 v[16:31], v[48:51], v[150:153], v[16:31]
	s_waitcnt lgkmcnt(0)
	v_mfma_f32_32x32x16_bf16 v[0:15], v[52:55], v[150:153], v[0:15]
	ds_read_b128 v[48:51], v200 offset:4096
	ds_read_b128 v[52:55], v200 offset:4608
	s_waitcnt lgkmcnt(1)
	v_mfma_f32_32x32x16_bf16 v[16:31], v[48:51], v[142:145], v[16:31]
	s_waitcnt lgkmcnt(0)
	v_mfma_f32_32x32x16_bf16 v[0:15], v[52:55], v[142:145], v[0:15]
	ds_read_b128 v[48:51], v200 offset:6144
	ds_read_b128 v[52:55], v200 offset:6656
	s_waitcnt lgkmcnt(1)
	v_mfma_f32_32x32x16_bf16 v[16:31], v[48:51], v[134:137], v[16:31]
	v_lshl_add_u64 v[48:49], v[188:189], 0, s[22:23]
	v_lshl_add_u64 v[50:51], v[186:187], 0, s[26:27]
	s_waitcnt lgkmcnt(0)
	v_mfma_f32_32x32x16_bf16 v[0:15], v[52:55], v[134:137], v[0:15]
	s_nop 15
	s_nop 7
	s_waitcnt vmcnt(0) lgkmcnt(0)
	s_barrier
	s_mov_b32 s21, m0
	s_mov_b32 m0, s5
	s_nop 0
	global_load_lds_dwordx4 v[48:49], off
	s_mov_b32 m0, s21
	s_nop 0
	s_mov_b32 s21, m0
	s_mov_b32 m0, s20
	s_nop 0
	global_load_lds_dwordx4 v[50:51], off
	s_mov_b32 m0, s21
	ds_read_b128 v[80:83], v200 offset:8192
	ds_read_b128 v[166:169], v200 offset:8704
	ds_read_b128 v[170:173], v200 offset:10240
	ds_read_b128 v[162:165], v200 offset:10752
	ds_read_b128 v[124:127], v200 offset:12288
	ds_read_b128 v[120:123], v200 offset:12800
	ds_read_b128 v[116:119], v200 offset:14336
	ds_read_b128 v[112:115], v200 offset:14848
	s_waitcnt vmcnt(2) lgkmcnt(0)
	s_barrier
	s_cbranch_scc0 .LBB0_449
	s_setprio 1
